# sample-attention K tile shared across the 4 waves of a key split (quarter loads + LDS double buffer + one barrier per step), placeholder nops removed
# speedup vs baseline: 1.0119x; 1.0028x over previous
; __device__ __forceinline__ void sattn_unit(const Args& a, LAS unsigned char* lds, const LAS float* bt, int db, int h, int t, int tid, int wave, int lane) {
;     ...
;     for (int it = 0; it < nf; ++it) {
;         const int key0 = __builtin_amdgcn_readfirstlane((tile0 + it) * 32);
;         bf16x8 kf[4]; bf16x8 vf[2][2];
;         SA_CVT();
;         if (it + 1 < nf) SA_LOAD(key0 + 32);
.LBB0_295:
	ds_write_b128 v172, v[64:67] offset:40960
	ds_write_b128 v172, v[68:71] offset:42048
	s_waitcnt lgkmcnt(0)
	s_barrier
	ds_read_b128 v[108:111], v170 offset:40960
	ds_read_b128 v[104:107], v170 offset:40976
	ds_read_b128 v[100:103], v170 offset:41024
	ds_read_b128 v[96:99], v170 offset:41040
	ds_read_b128 v[44:47], v170 offset:41088
	ds_read_b128 v[40:43], v170 offset:41104
	ds_read_b128 v[36:39], v170 offset:41152
	ds_read_b128 v[32:35], v170 offset:41168
	v_add_u32_e32 v170, s32, v170
	v_add_u32_e32 v172, s32, v172
	s_sub_i32 s32, 0, s32
	s_add_i32 s0, s96, s35
	s_lshl_b32 vcc_lo, s0, 5
	s_add_i32 s35, s35, 1
	s_cmp_ge_u32 s35, s97
	s_cbranch_scc1 .LBB0_297
	s_add_i32 s0, s30, vcc_lo
	s_ashr_i32 s1, s0, 31
	s_lshl_b64 s[0:1], s[0:1], 12
	s_lshl_b32 s14, s5, 2
	s_or_b32 s0, s0, s14
	s_add_u32 s48, s93, s0
	s_addc_u32 s49, s89, s1
	s_add_u32 s48, s48, s81
	s_addc_u32 s49, s49, 0
	s_add_u32 s0, s42, s0
	s_addc_u32 s1, s43, s1
	v_lshl_add_u64 v[64:65], v[112:113], 2, s[48:49]
	v_lshl_add_u64 v[68:69], v[120:121], 2, s[48:49]
	global_load_dwordx4 v[64:67], v[64:65], off
	s_nop 0
	global_load_dwordx4 v[68:71], v[68:69], off
	s_nop 0
	global_load_dword v176, v134, s[0:1]
	global_load_dword v174, v134, s[0:1] offset:128
	s_add_u32 s14, s0, 0x10000
	s_addc_u32 s15, s1, 0
	global_load_dword v175, v134, s[14:15]
	global_load_dword v173, v136, s[14:15]
	s_add_u32 s48, s0, 0x1000
	s_addc_u32 s49, s1, 0
	global_load_dword v179, v134, s[48:49]
	global_load_dword v177, v136, s[48:49]
	s_add_u32 s14, s0, 0x11000
	s_addc_u32 s15, s1, 0
	global_load_dword v178, v134, s[14:15]
	global_load_dword v180, v136, s[14:15]
	s_add_u32 s48, s0, 0x2000
	s_addc_u32 s49, s1, 0
	global_load_dword v195, v134, s[48:49]
	global_load_dword v184, v136, s[48:49]
	s_add_u32 s14, s0, 0x12000
	s_addc_u32 s15, s1, 0
	global_load_dword v186, v134, s[14:15]
	global_load_dword v183, v136, s[14:15]
	s_add_u32 s48, s0, 0x3000
	s_addc_u32 s49, s1, 0
	global_load_dword v204, v134, s[48:49]
	global_load_dword v200, v136, s[48:49]
	s_add_u32 s14, s0, 0x13000
	s_addc_u32 s15, s1, 0
	global_load_dword v202, v134, s[14:15]
	global_load_dword v207, v136, s[14:15]
	s_add_u32 s48, s0, 0x8000
	s_addc_u32 s49, s1, 0
	global_load_dword v219, v134, s[48:49]
	global_load_dword v216, v136, s[48:49]
	s_add_u32 s14, s0, 0x18000
	s_addc_u32 s15, s1, 0
	global_load_dword v218, v134, s[14:15]
	global_load_dword v214, v136, s[14:15]
	s_add_u32 s48, s0, 0x9000
	s_addc_u32 s49, s1, 0
	global_load_dword v228, v134, s[48:49]
	global_load_dword v224, v136, s[48:49]
	s_add_u32 s14, s0, 0x19000
	s_addc_u32 s15, s1, 0
	global_load_dword v226, v134, s[14:15]
	global_load_dword v231, v136, s[14:15]
	s_add_u32 s48, s0, 0xa000
	s_addc_u32 s49, s1, 0
	global_load_dword v239, v134, s[48:49]
	global_load_dword v237, v136, s[48:49]
	s_add_u32 s14, s0, 0x1a000
	s_addc_u32 s15, s1, 0
	global_load_dword v238, v134, s[14:15]
	global_load_dword v236, v136, s[14:15]
	s_add_u32 s48, s0, 0xb000
	s_addc_u32 s49, s1, 0
	global_load_dword v242, v134, s[48:49]
	global_load_dword v240, v136, s[48:49]
	s_add_u32 s14, s0, 0x1b000
	s_addc_u32 s15, s1, 0
	global_load_dword v241, v134, s[14:15]
	global_load_dword v243, v136, s[14:15]
